# single B half-tile stage move (second -> third segment) in the UP and the DOWN/w_o main loops (not w_in); waits vmcnt 8->6, relaxed 24->22 in DOWN; on top of v72
# speedup vs baseline: 1.0120x; 1.0120x over previous
.Lrx_skip_2:
	s_waitcnt vmcnt(24)
	s_waitcnt lgkmcnt(0)
	s_barrier
	s_setprio 1
	v_mfma_f32_16x16x32_bf16 v[126:129], v[130:133], v[186:189], v[126:129]
	v_mfma_f32_16x16x32_bf16 v[122:125], v[138:141], v[186:189], v[122:125]
	v_mfma_f32_16x16x32_bf16 v[110:113], v[130:133], v[220:223], v[110:113]
	v_mfma_f32_16x16x32_bf16 v[106:109], v[138:141], v[220:223], v[106:109]
	v_mfma_f32_16x16x32_bf16 v[94:97], v[130:133], v[228:231], v[94:97]
	v_mfma_f32_16x16x32_bf16 v[90:93], v[138:141], v[228:231], v[90:93]
	v_mfma_f32_16x16x32_bf16 v[78:81], v[130:133], v[236:239], v[78:81]
	v_mfma_f32_16x16x32_bf16 v[74:77], v[138:141], v[236:239], v[74:77]
	v_mfma_f32_16x16x32_bf16 v[126:129], v[134:137], v[190:193], v[126:129]
	v_mfma_f32_16x16x32_bf16 v[122:125], v[142:145], v[190:193], v[122:125]
	v_mfma_f32_16x16x32_bf16 v[110:113], v[134:137], v[224:227], v[110:113]
	v_mfma_f32_16x16x32_bf16 v[106:109], v[142:145], v[224:227], v[106:109]
	v_mfma_f32_16x16x32_bf16 v[94:97], v[134:137], v[232:235], v[94:97]
	v_mfma_f32_16x16x32_bf16 v[90:93], v[142:145], v[232:235], v[90:93]
	v_mfma_f32_16x16x32_bf16 v[78:81], v[134:137], v[240:243], v[78:81]
	v_mfma_f32_16x16x32_bf16 v[74:77], v[142:145], v[240:243], v[74:77]
	s_setprio 0
	s_setprio 1
	v_mfma_f32_16x16x32_bf16 v[118:121], v[146:149], v[186:189], v[118:121]
	v_mfma_f32_16x16x32_bf16 v[114:117], v[154:157], v[186:189], v[114:117]
	v_mfma_f32_16x16x32_bf16 v[102:105], v[146:149], v[220:223], v[102:105]
	v_mfma_f32_16x16x32_bf16 v[98:101], v[154:157], v[220:223], v[98:101]
	v_mfma_f32_16x16x32_bf16 v[86:89], v[146:149], v[228:231], v[86:89]
	v_mfma_f32_16x16x32_bf16 v[82:85], v[154:157], v[228:231], v[82:85]
	v_mfma_f32_16x16x32_bf16 v[70:73], v[146:149], v[236:239], v[70:73]
	v_mfma_f32_16x16x32_bf16 v[66:69], v[154:157], v[236:239], v[66:69]
	v_mfma_f32_16x16x32_bf16 v[118:121], v[150:153], v[190:193], v[118:121]
	v_mfma_f32_16x16x32_bf16 v[114:117], v[182:185], v[190:193], v[114:117]
	v_mfma_f32_16x16x32_bf16 v[102:105], v[150:153], v[224:227], v[102:105]
	v_mfma_f32_16x16x32_bf16 v[98:101], v[182:185], v[224:227], v[98:101]
	v_mfma_f32_16x16x32_bf16 v[86:89], v[150:153], v[232:235], v[86:89]
	v_mfma_f32_16x16x32_bf16 v[82:85], v[182:185], v[232:235], v[82:85]
	v_mfma_f32_16x16x32_bf16 v[70:73], v[150:153], v[240:243], v[70:73]
	v_mfma_f32_16x16x32_bf16 v[66:69], v[182:185], v[240:243], v[66:69]
	s_setprio 0
	s_barrier
	ds_read_b128 v[186:189], v216 offset:16384
	ds_read_b128 v[190:193], v216 offset:17408
	ds_read_b128 v[220:223], v216 offset:18432
	ds_read_b128 v[224:227], v216 offset:19456
	ds_read_b128 v[228:231], v216 offset:20480
	ds_read_b128 v[232:235], v216 offset:21504
	ds_read_b128 v[236:239], v216 offset:22528
	ds_read_b128 v[240:243], v216 offset:23552
	s_mov_b32 m0, s65
	s_nop 0
	global_load_lds_dwordx4 v209, s[62:63]
	s_nop 0
	s_mov_b32 m0, s66
	s_nop 0
	global_load_lds_dwordx4 v211, s[62:63]
	s_nop 0
	s_mov_b32 m0, s64
	s_nop 0
	global_load_lds_dwordx4 v159, s[60:61]
	s_nop 0
	s_mov_b32 m0, s69
	s_nop 0
	global_load_lds_dwordx4 v210, s[60:61]
	s_cmp_lg_u32 s9, 0
	s_cbranch_scc1 .Lrx_skip_3
	s_waitcnt vmcnt(6)
.Lrx_skip_3:
	s_waitcnt vmcnt(22)
	s_waitcnt lgkmcnt(0)
	s_barrier
	s_setprio 1
	v_mfma_f32_16x16x32_bf16 v[62:65], v[130:133], v[186:189], v[62:65]
	v_mfma_f32_16x16x32_bf16 v[58:61], v[138:141], v[186:189], v[58:61]
	v_mfma_f32_16x16x32_bf16 v[46:49], v[130:133], v[220:223], v[46:49]
	v_mfma_f32_16x16x32_bf16 v[42:45], v[138:141], v[220:223], v[42:45]
	v_mfma_f32_16x16x32_bf16 v[30:33], v[130:133], v[228:231], v[30:33]
	v_mfma_f32_16x16x32_bf16 v[26:29], v[138:141], v[228:231], v[26:29]
	v_mfma_f32_16x16x32_bf16 v[14:17], v[130:133], v[236:239], v[14:17]
	v_mfma_f32_16x16x32_bf16 v[10:13], v[138:141], v[236:239], v[10:13]
	v_mfma_f32_16x16x32_bf16 v[62:65], v[134:137], v[190:193], v[62:65]
	v_mfma_f32_16x16x32_bf16 v[58:61], v[142:145], v[190:193], v[58:61]
	v_mfma_f32_16x16x32_bf16 v[46:49], v[134:137], v[224:227], v[46:49]
	v_mfma_f32_16x16x32_bf16 v[42:45], v[142:145], v[224:227], v[42:45]
	v_mfma_f32_16x16x32_bf16 v[30:33], v[134:137], v[232:235], v[30:33]
	v_mfma_f32_16x16x32_bf16 v[26:29], v[142:145], v[232:235], v[26:29]
	v_mfma_f32_16x16x32_bf16 v[14:17], v[134:137], v[240:243], v[14:17]
	v_mfma_f32_16x16x32_bf16 v[10:13], v[142:145], v[240:243], v[10:13]
	s_setprio 0
	s_setprio 1
	v_mfma_f32_16x16x32_bf16 v[54:57], v[146:149], v[186:189], v[54:57]
	v_mfma_f32_16x16x32_bf16 v[50:53], v[154:157], v[186:189], v[50:53]
	v_mfma_f32_16x16x32_bf16 v[38:41], v[146:149], v[220:223], v[38:41]
	v_mfma_f32_16x16x32_bf16 v[34:37], v[154:157], v[220:223], v[34:37]
	v_mfma_f32_16x16x32_bf16 v[22:25], v[146:149], v[228:231], v[22:25]
	v_mfma_f32_16x16x32_bf16 v[18:21], v[154:157], v[228:231], v[18:21]
	v_mfma_f32_16x16x32_bf16 v[6:9], v[146:149], v[236:239], v[6:9]
	v_mfma_f32_16x16x32_bf16 v[2:5], v[154:157], v[236:239], v[2:5]
	v_mfma_f32_16x16x32_bf16 v[54:57], v[150:153], v[190:193], v[54:57]
	v_mfma_f32_16x16x32_bf16 v[50:53], v[182:185], v[190:193], v[50:53]
	v_mfma_f32_16x16x32_bf16 v[38:41], v[150:153], v[224:227], v[38:41]
	v_mfma_f32_16x16x32_bf16 v[34:37], v[182:185], v[224:227], v[34:37]
	v_mfma_f32_16x16x32_bf16 v[22:25], v[150:153], v[232:235], v[22:25]
	v_mfma_f32_16x16x32_bf16 v[18:21], v[182:185], v[232:235], v[18:21]
	v_mfma_f32_16x16x32_bf16 v[6:9], v[150:153], v[240:243], v[6:9]
	v_mfma_f32_16x16x32_bf16 v[2:5], v[182:185], v[240:243], v[2:5]
	s_setprio 0
	s_barrier
	v_add_u32_e32 v142, 0x18000, v215
	v_add_u32_e32 v182, 0x1c000, v215
	ds_read_b128 v[130:133], v142
	ds_read_b128 v[134:137], v142 offset:1024
	ds_read_b128 v[138:141], v142 offset:2048
	ds_read_b128 v[142:145], v142 offset:3072
	ds_read_b128 v[146:149], v182
	ds_read_b128 v[150:153], v182 offset:1024
	ds_read_b128 v[154:157], v182 offset:2048
	ds_read_b128 v[182:185], v182 offset:3072
	ds_read_b128 v[186:189], v216 offset:32768
	ds_read_b128 v[190:193], v216 offset:33792
	ds_read_b128 v[220:223], v216 offset:34816
	ds_read_b128 v[224:227], v216 offset:35840
	ds_read_b128 v[228:231], v216 offset:36864
	ds_read_b128 v[232:235], v216 offset:37888
	ds_read_b128 v[236:239], v216 offset:38912
	ds_read_b128 v[240:243], v216 offset:39936
	s_add_u32 s62, s62, s15
	s_addc_u32 s63, s63, 0
	s_mov_b32 m0, s67
	s_nop 0
	global_load_lds_dwordx4 v209, s[62:63]
	s_nop 0
	s_mov_b32 m0, s68
	s_nop 0
	global_load_lds_dwordx4 v211, s[62:63]
	s_nop 0
	s_add_u32 s18, s60, s15
	s_addc_u32 s19, s61, 0
	s_mov_b32 m0, s70
	s_nop 0
	global_load_lds_dwordx4 v159, s[18:19]
	s_nop 0
	s_mov_b32 m0, s71
	s_nop 0
	global_load_lds_dwordx4 v210, s[18:19]
	s_cmp_lg_u32 s9, 0
	s_cbranch_scc1 .Lrx_skip_4
	s_waitcnt vmcnt(8)
